# instruction selection in the issue-bound attention loop: P*V operands read straight into MFMA register quads (64 ds_read_b64 replace 32 ds_read2st64_b64 + 97 v_mov)
# speedup vs baseline: 1.0085x; 1.0085x over previous
; __device__ __forceinline__ unsigned pk2(float lo, float hi) { unsigned r; asm("v_cvt_pk_bf16_f32 %0, %1, %2" : "=v"(r) : "v"(lo), "v"(hi)); return r; }
; __device__ __forceinline__ void na_item(const Params& p, int b, int hd, int r, int j, int lane, const float* rpl, const unsigned char* Vl) {
;     ...
;     float mx = -1.0e30f;
; #pragma unroll
;     for (int mt = 0; mt < 16; ++mt)
; #pragma unroll
;         for (int jj = 0; jj < 4; ++jj) { const int kcol = kstart + (mt & 1) * 16 + 4 * fq + jj; const bool valid = (kcol >= wstart) && (kcol < wstart + 16);
;             const int dc = min(max(kcol - qc + 15, 0), 30), dr = rs + (mt >> 1) - r + 7;
;             const float sc = valid ? accS[mt][jj] * 0.125f + rp[dr * 31 + dc] : -1.0e30f; accS[mt][jj] = sc; mx = fmaxf(mx, sc); }
;     mx = fmaxf(mx, __shfl_xor(mx, 16)); mx = fmaxf(mx, __shfl_xor(mx, 32));
;     float sum = 0.f;
;     bf16x8 pf[8];
; #pragma unroll
;     for (int ks = 0; ks < 8; ++ks) { float e[8];
; #pragma unroll
;         for (int i = 0; i < 8; ++i) { e[i] = __expf(accS[2 * ks + (i >> 2)][i & 3] - mx); sum += e[i]; }
;         u32x4 wv; wv.x = pk2(e[0], e[1]); wv.y = pk2(e[2], e[3]); wv.z = pk2(e[4], e[5]); wv.w = pk2(e[6], e[7]); pf[ks] = __builtin_bit_cast(bf16x8, wv); }
;     sum += __shfl_xor(sum, 16); sum += __shfl_xor(sum, 32);
.LBB0_329:
	v_max3_f32 v8, v150, s57, v149
	v_max3_f32 v8, v8, v69, v68
	v_max3_f32 v8, v8, v71, v70
	v_max3_f32 v8, v8, v65, v64
	v_max3_f32 v8, v8, v67, v66
	v_max3_f32 v8, v8, v61, v60
	v_max3_f32 v8, v8, v63, v62
	v_max3_f32 v8, v8, v57, v56
	v_max3_f32 v8, v8, v59, v58
	v_max3_f32 v8, v8, v53, v52
	v_max3_f32 v8, v8, v55, v54
	v_max3_f32 v8, v8, v49, v48
	v_max3_f32 v8, v8, v51, v50
	v_max3_f32 v8, v8, v45, v44
	v_max3_f32 v8, v8, v47, v46
	v_max3_f32 v8, v8, v41, v40
	v_max3_f32 v8, v8, v43, v42
	v_max3_f32 v8, v8, v37, v36
	v_max3_f32 v8, v8, v39, v38
	v_max3_f32 v8, v8, v33, v32
	v_max3_f32 v8, v8, v35, v34
	v_max3_f32 v8, v8, v29, v28
	v_max3_f32 v8, v8, v31, v30
	v_max3_f32 v8, v8, v161, v160
	v_max3_f32 v8, v8, v163, v162
	v_max3_f32 v8, v8, v165, v164
	v_max3_f32 v8, v8, v167, v166
	v_max3_f32 v8, v8, v169, v168
	v_max3_f32 v8, v8, v171, v170
	v_max3_f32 v8, v8, v152, v151
	v_max3_f32 v8, v8, v154, v153
	v_max3_f32 v8, v8, v156, v155
	ds_bpermute_b32 v9, v108, v8
	s_add_i32 s58, s58, 2
	v_lshl_add_u64 v[200:201], v[86:87], 0, s[2:3]
	v_add_u32_e32 v147, 2, v147
	v_add_u32_e32 v148, -2, v148
	s_waitcnt lgkmcnt(0)
	v_max_f32_e32 v9, v9, v9
	v_max_f32_e32 v8, v8, v9
	ds_bpermute_b32 v9, v109, v8
	v_lshl_add_u64 v[84:85], v[84:85], 0, s[20:21]
	v_lshl_add_u64 v[86:87], v[86:87], 0, s[22:23]
	s_cmp_eq_u32 s62, 16
	s_waitcnt lgkmcnt(0)
	v_max_f32_e32 v9, v9, v9
	v_max_f32_e32 v157, v8, v9
	v_sub_f32_e32 v8, v150, v157
	v_sub_f32_e32 v9, v149, v157
	v_mul_f32_e32 v8, 0x3fb8aa3b, v8
	v_sub_f32_e32 v10, v69, v157
	v_mul_f32_e32 v9, 0x3fb8aa3b, v9
	v_exp_f32_e32 v8, v8
	v_sub_f32_e32 v11, v68, v157
	v_mul_f32_e32 v10, 0x3fb8aa3b, v10
	v_exp_f32_e32 v9, v9
	v_sub_f32_e32 v12, v71, v157
	v_mul_f32_e32 v11, 0x3fb8aa3b, v11
	v_exp_f32_e32 v10, v10
	v_mul_f32_e32 v12, 0x3fb8aa3b, v12
	v_exp_f32_e32 v11, v11
	v_sub_f32_e32 v14, v70, v157
	v_add_f32_e32 v13, 0, v8
	v_exp_f32_e32 v12, v12
	v_mul_f32_e32 v14, 0x3fb8aa3b, v14
	v_sub_f32_e32 v15, v65, v157
	v_add_f32_e32 v13, v9, v13
	v_exp_f32_e32 v14, v14
	v_mul_f32_e32 v15, 0x3fb8aa3b, v15
	v_sub_f32_e32 v16, v64, v157
	v_add_f32_e32 v13, v10, v13
	v_exp_f32_e32 v15, v15
	v_mul_f32_e32 v16, 0x3fb8aa3b, v16
	v_add_f32_e32 v13, v11, v13
	v_exp_f32_e32 v16, v16
	v_add_f32_e32 v13, v12, v13
	v_cvt_pk_bf16_f32 v8, v8, v9
	v_cvt_pk_bf16_f32 v9, v10, v11
	v_cvt_pk_bf16_f32 v10, v12, v14
	v_sub_f32_e32 v12, v67, v157
	v_add_f32_e32 v13, v14, v13
	v_mul_f32_e32 v12, 0x3fb8aa3b, v12
	v_sub_f32_e32 v14, v66, v157
	v_add_f32_e32 v13, v15, v13
	v_cvt_pk_bf16_f32 v11, v15, v16
	v_exp_f32_e32 v12, v12
	v_mul_f32_e32 v14, 0x3fb8aa3b, v14
	v_sub_f32_e32 v15, v61, v157
	v_add_f32_e32 v13, v16, v13
	v_exp_f32_e32 v14, v14
	v_mul_f32_e32 v15, 0x3fb8aa3b, v15
	v_sub_f32_e32 v16, v60, v157
	v_exp_f32_e32 v15, v15
	v_mul_f32_e32 v16, 0x3fb8aa3b, v16
	v_sub_f32_e32 v17, v63, v157
	v_exp_f32_e32 v16, v16
	v_mul_f32_e32 v17, 0x3fb8aa3b, v17
	v_sub_f32_e32 v18, v62, v157
	v_add_f32_e32 v13, v12, v13
	v_exp_f32_e32 v17, v17
	v_mul_f32_e32 v18, 0x3fb8aa3b, v18
	v_sub_f32_e32 v19, v57, v157
	v_add_f32_e32 v13, v14, v13
	v_exp_f32_e32 v18, v18
	v_mul_f32_e32 v19, 0x3fb8aa3b, v19
	v_sub_f32_e32 v20, v56, v157
	v_add_f32_e32 v13, v15, v13
	v_exp_f32_e32 v19, v19
	v_mul_f32_e32 v20, 0x3fb8aa3b, v20
	v_add_f32_e32 v13, v16, v13
	v_exp_f32_e32 v20, v20
	v_add_f32_e32 v13, v17, v13
	v_add_f32_e32 v13, v18, v13
	v_add_f32_e32 v13, v19, v13
	v_add_f32_e32 v21, v20, v13
	v_cvt_pk_bf16_f32 v13, v15, v16
	v_sub_f32_e32 v16, v59, v157
	v_mul_f32_e32 v16, 0x3fb8aa3b, v16
	v_exp_f32_e32 v16, v16
	v_cvt_pk_bf16_f32 v12, v12, v14
	v_cvt_pk_bf16_f32 v14, v17, v18
	v_sub_f32_e32 v17, v58, v157
	v_mul_f32_e32 v17, 0x3fb8aa3b, v17
	v_sub_f32_e32 v18, v53, v157
	v_cvt_pk_bf16_f32 v15, v19, v20
	v_exp_f32_e32 v17, v17
	v_mul_f32_e32 v18, 0x3fb8aa3b, v18
	v_sub_f32_e32 v19, v52, v157
	v_exp_f32_e32 v18, v18
	v_mul_f32_e32 v19, 0x3fb8aa3b, v19
	v_add_f32_e32 v20, v16, v21
	v_sub_f32_e32 v21, v55, v157
	v_exp_f32_e32 v19, v19
	v_mul_f32_e32 v21, 0x3fb8aa3b, v21
	v_sub_f32_e32 v22, v54, v157
	v_exp_f32_e32 v21, v21
	v_mul_f32_e32 v22, 0x3fb8aa3b, v22
	v_sub_f32_e32 v23, v49, v157
	v_add_f32_e32 v20, v17, v20
	v_exp_f32_e32 v22, v22
	v_mul_f32_e32 v23, 0x3fb8aa3b, v23
	v_sub_f32_e32 v24, v48, v157
	v_add_f32_e32 v20, v18, v20
	v_exp_f32_e32 v23, v23
	v_mul_f32_e32 v24, 0x3fb8aa3b, v24
	v_add_f32_e32 v20, v19, v20
	v_exp_f32_e32 v24, v24
	v_add_f32_e32 v20, v21, v20
	v_cvt_pk_bf16_f32 v16, v16, v17
	v_cvt_pk_bf16_f32 v17, v18, v19
	v_cvt_pk_bf16_f32 v18, v21, v22
	v_sub_f32_e32 v21, v51, v157
	v_add_f32_e32 v20, v22, v20
	v_mul_f32_e32 v21, 0x3fb8aa3b, v21
	v_sub_f32_e32 v22, v50, v157
	v_add_f32_e32 v20, v23, v20
	v_cvt_pk_bf16_f32 v19, v23, v24
	v_exp_f32_e32 v21, v21
	v_mul_f32_e32 v22, 0x3fb8aa3b, v22
	v_sub_f32_e32 v23, v45, v157
	v_add_f32_e32 v20, v24, v20
	v_exp_f32_e32 v22, v22
	v_mul_f32_e32 v23, 0x3fb8aa3b, v23
	v_sub_f32_e32 v24, v44, v157
	v_exp_f32_e32 v23, v23
	v_mul_f32_e32 v24, 0x3fb8aa3b, v24
	v_sub_f32_e32 v25, v47, v157
	v_exp_f32_e32 v24, v24
	v_mul_f32_e32 v25, 0x3fb8aa3b, v25
	v_sub_f32_e32 v26, v46, v157
	v_add_f32_e32 v20, v21, v20
	v_exp_f32_e32 v25, v25
	v_mul_f32_e32 v26, 0x3fb8aa3b, v26
	v_sub_f32_e32 v27, v41, v157
	v_add_f32_e32 v20, v22, v20
	v_exp_f32_e32 v26, v26
	v_mul_f32_e32 v27, 0x3fb8aa3b, v27
	v_sub_f32_e32 v40, v40, v157
	v_add_f32_e32 v20, v23, v20
	v_exp_f32_e32 v27, v27
	v_mul_f32_e32 v40, 0x3fb8aa3b, v40
	v_add_f32_e32 v20, v24, v20
	v_exp_f32_e32 v40, v40
	v_add_f32_e32 v20, v25, v20
	v_add_f32_e32 v20, v26, v20
	v_add_f32_e32 v20, v27, v20
	v_add_f32_e32 v41, v40, v20
	v_cvt_pk_bf16_f32 v20, v21, v22
; __device__ __forceinline__ unsigned pk2(float lo, float hi) { unsigned r; asm("v_cvt_pk_bf16_f32 %0, %1, %2" : "=v"(r) : "v"(lo), "v"(hi)); return r; }
; __device__ __forceinline__ void na_item(const Params& p, int b, int hd, int r, int j, int lane, const float* rpl, const unsigned char* Vl) {
;     ...
;     for (int ks = 0; ks < 8; ++ks) { float e[8];
; #pragma unroll
;         for (int i = 0; i < 8; ++i) { e[i] = __expf(accS[2 * ks + (i >> 2)][i & 3] - mx); sum += e[i]; }
;         u32x4 wv; wv.x = pk2(e[0], e[1]); wv.y = pk2(e[2], e[3]); wv.z = pk2(e[4], e[5]); wv.w = pk2(e[6], e[7]); pf[ks] = __builtin_bit_cast(bf16x8, wv); }
;     sum += __shfl_xor(sum, 16); sum += __shfl_xor(sum, 32);
;     const float rsum = 1.0f / sum;
	v_cvt_pk_bf16_f32 v21, v23, v24
	v_sub_f32_e32 v24, v43, v157
	v_cvt_pk_bf16_f32 v22, v25, v26
	v_mul_f32_e32 v24, 0x3fb8aa3b, v24
	v_sub_f32_e32 v25, v42, v157
	v_exp_f32_e32 v24, v24
	v_mul_f32_e32 v25, 0x3fb8aa3b, v25
	v_sub_f32_e32 v26, v37, v157
	v_cvt_pk_bf16_f32 v23, v27, v40
	v_exp_f32_e32 v25, v25
	v_mul_f32_e32 v26, 0x3fb8aa3b, v26
	v_sub_f32_e32 v27, v36, v157
	v_exp_f32_e32 v26, v26
	v_mul_f32_e32 v27, 0x3fb8aa3b, v27
	v_sub_f32_e32 v37, v39, v157
	v_exp_f32_e32 v27, v27
	v_mul_f32_e32 v37, 0x3fb8aa3b, v37
	v_sub_f32_e32 v38, v38, v157
	v_add_f32_e32 v36, v24, v41
	v_exp_f32_e32 v37, v37
	v_mul_f32_e32 v38, 0x3fb8aa3b, v38
	v_sub_f32_e32 v33, v33, v157
	v_add_f32_e32 v36, v25, v36
	v_exp_f32_e32 v38, v38
	v_mul_f32_e32 v33, 0x3fb8aa3b, v33
	v_sub_f32_e32 v32, v32, v157
	v_add_f32_e32 v36, v26, v36
	v_exp_f32_e32 v33, v33
	v_mul_f32_e32 v32, 0x3fb8aa3b, v32
	v_add_f32_e32 v36, v27, v36
	v_exp_f32_e32 v32, v32
	v_add_f32_e32 v36, v37, v36
	v_add_f32_e32 v36, v38, v36
	v_add_f32_e32 v36, v33, v36
	v_add_f32_e32 v36, v32, v36
	v_cvt_pk_bf16_f32 v24, v24, v25
	v_cvt_pk_bf16_f32 v25, v26, v27
	v_cvt_pk_bf16_f32 v27, v33, v32
	v_sub_f32_e32 v32, v35, v157
	v_mul_f32_e32 v32, 0x3fb8aa3b, v32
	v_sub_f32_e32 v33, v34, v157
	v_exp_f32_e32 v32, v32
	v_mul_f32_e32 v33, 0x3fb8aa3b, v33
	v_sub_f32_e32 v29, v29, v157
	v_exp_f32_e32 v33, v33
	v_mul_f32_e32 v29, 0x3fb8aa3b, v29
	v_sub_f32_e32 v28, v28, v157
	v_exp_f32_e32 v29, v29
	v_mul_f32_e32 v28, 0x3fb8aa3b, v28
	v_sub_f32_e32 v31, v31, v157
	v_exp_f32_e32 v34, v28
	v_mul_f32_e32 v31, 0x3fb8aa3b, v31
	v_sub_f32_e32 v30, v30, v157
	v_add_f32_e32 v28, v32, v36
	v_exp_f32_e32 v31, v31
	v_mul_f32_e32 v30, 0x3fb8aa3b, v30
	v_sub_f32_e32 v35, v161, v157
	v_add_f32_e32 v28, v33, v28
	v_exp_f32_e32 v30, v30
	v_mul_f32_e32 v35, 0x3fb8aa3b, v35
	v_sub_f32_e32 v36, v160, v157
	v_add_f32_e32 v28, v29, v28
	v_exp_f32_e32 v35, v35
	v_mul_f32_e32 v36, 0x3fb8aa3b, v36
	v_add_f32_e32 v28, v34, v28
	v_exp_f32_e32 v36, v36
	v_add_f32_e32 v28, v31, v28
	v_add_f32_e32 v28, v30, v28
	v_cvt_pk_bf16_f32 v30, v31, v30
	v_sub_f32_e32 v31, v163, v157
	v_add_f32_e32 v28, v35, v28
	v_mul_f32_e32 v31, 0x3fb8aa3b, v31
	v_cvt_pk_bf16_f32 v26, v37, v38
	v_add_f32_e32 v37, v36, v28
	v_cvt_pk_bf16_f32 v28, v32, v33
	v_exp_f32_e32 v32, v31
	v_sub_f32_e32 v31, v162, v157
	v_mul_f32_e32 v31, 0x3fb8aa3b, v31
	v_exp_f32_e32 v33, v31
	v_sub_f32_e32 v31, v165, v157
	v_mul_f32_e32 v31, 0x3fb8aa3b, v31
	v_cvt_pk_bf16_f32 v29, v29, v34
	v_exp_f32_e32 v34, v31
	v_sub_f32_e32 v31, v164, v157
	v_mul_f32_e32 v31, 0x3fb8aa3b, v31
	v_exp_f32_e32 v38, v31
	v_add_f32_e32 v31, v32, v37
	v_sub_f32_e32 v37, v167, v157
	v_mul_f32_e32 v37, 0x3fb8aa3b, v37
	v_exp_f32_e32 v39, v37
	v_sub_f32_e32 v37, v166, v157
	v_mul_f32_e32 v37, 0x3fb8aa3b, v37
	v_exp_f32_e32 v40, v37
	v_sub_f32_e32 v37, v169, v157
	v_mul_f32_e32 v37, 0x3fb8aa3b, v37
	v_exp_f32_e32 v41, v37
	v_sub_f32_e32 v37, v168, v157
	v_mul_f32_e32 v37, 0x3fb8aa3b, v37
	v_exp_f32_e32 v42, v37
	v_sub_f32_e32 v37, v171, v157
	v_mul_f32_e32 v37, 0x3fb8aa3b, v37
	v_exp_f32_e32 v43, v37
	v_sub_f32_e32 v37, v170, v157
	v_mul_f32_e32 v37, 0x3fb8aa3b, v37
	v_exp_f32_e32 v44, v37
	v_sub_f32_e32 v37, v152, v157
	v_mul_f32_e32 v37, 0x3fb8aa3b, v37
	v_add_f32_e32 v31, v33, v31
	v_exp_f32_e32 v45, v37
	v_sub_f32_e32 v37, v151, v157
	v_add_f32_e32 v31, v34, v31
	v_mul_f32_e32 v37, 0x3fb8aa3b, v37
	v_add_f32_e32 v31, v38, v31
	v_exp_f32_e32 v46, v37
	v_sub_f32_e32 v37, v154, v157
	v_add_f32_e32 v31, v39, v31
	v_mul_f32_e32 v37, 0x3fb8aa3b, v37
	v_add_f32_e32 v31, v40, v31
	v_exp_f32_e32 v47, v37
	v_sub_f32_e32 v37, v153, v157
	v_add_f32_e32 v31, v41, v31
	v_mul_f32_e32 v37, 0x3fb8aa3b, v37
	v_add_f32_e32 v31, v42, v31
	v_exp_f32_e32 v48, v37
	v_sub_f32_e32 v37, v156, v157
	v_add_f32_e32 v31, v43, v31
	v_mul_f32_e32 v37, 0x3fb8aa3b, v37
	v_add_f32_e32 v31, v44, v31
	v_exp_f32_e32 v149, v37
	v_sub_f32_e32 v37, v155, v157
	v_add_f32_e32 v31, v45, v31
	v_mul_f32_e32 v37, 0x3fb8aa3b, v37
	v_add_f32_e32 v31, v46, v31
	v_exp_f32_e32 v158, v37
	v_add_f32_e32 v31, v47, v31
	v_add_f32_e32 v31, v48, v31
	v_add_f32_e32 v31, v149, v31
	v_add_f32_e32 v49, v158, v31
	ds_bpermute_b32 v50, v108, v49
	v_cvt_pk_bf16_f32 v31, v35, v36
	v_cvt_pk_bf16_f32 v37, v34, v38
	v_cvt_pk_bf16_f32 v38, v39, v40
	v_cvt_pk_bf16_f32 v36, v32, v33
	s_waitcnt lgkmcnt(0)
	v_add_f32_e32 v35, v49, v50
	ds_bpermute_b32 v40, v109, v35
	v_cvt_pk_bf16_f32 v32, v43, v44
	v_cvt_pk_bf16_f32 v39, v41, v42
	v_cvt_pk_bf16_f32 v33, v45, v46
	v_cvt_pk_bf16_f32 v34, v47, v48
	s_waitcnt lgkmcnt(0)
; __device__ __forceinline__ f32x4 mfma16(bf16x8 a, bf16x8 b, f32x4 c) { return __builtin_amdgcn_mfma_f32_16x16x32_bf16(a, b, c, 0, 0, 0); }
; __device__ __forceinline__ void na_item(const Params& p, int b, int hd, int r, int j, int lane, const float* rpl, const unsigned char* Vl) {
;     ...
;     const int ca = (((kstart >> 2) + fq) ^ fr) << 3, cb = (((kstart >> 2) + 4 + fq) ^ fr) << 3;
;     const int s0 = rs % 11;
; #pragma unroll
;     for (int dt = 0; dt < 4; ++dt) { f32x4 a = (f32x4){0.f, 0.f, 0.f, 0.f};
;         u32x2 va[8], vb[8];
; #pragma unroll
;         for (int ks = 0; ks < 8; ++ks) { int sl = s0 + ks; sl = (sl >= 11) ? sl - 11 : sl; const unsigned char* vp = Vl + sl * 8192 + (16 * dt + fr) * 128;
;             va[ks] = *(const u32x2*)(vp + ca); vb[ks] = *(const u32x2*)(vp + cb); }
; #pragma unroll
;         for (int ks = 0; ks < 8; ++ks) a = mfma16(mk8(va[ks], vb[ks]), pf[ks], a);
	v_add_f32_e32 v196, v35, v40
	v_mul_lo_u16_e32 v35, 47, v74
	v_lshrrev_b16_e32 v35, 9, v35
	v_mul_lo_u16_e32 v35, 11, v35
	v_sub_u16_e32 v35, v74, v35
	v_lshlrev_b32_sdwa v74, v124, v35 dst_sel:DWORD dst_unused:UNUSED_PAD src0_sel:DWORD src1_sel:BYTE_0
	v_add_u32_e32 v152, v120, v74
	v_add_u32_e32 v199, v152, v118
	v_add_u32_e32 v204, v152, v119
	ds_read_b64 v[40:41], v199 offset:32768
	ds_read_b64 v[42:43], v204 offset:32768
	ds_read_b64 v[44:45], v199 offset:34816
	ds_read_b64 v[46:47], v204 offset:34816
	v_cmp_gt_u16_sdwa vcc, v35, v125 src0_sel:BYTE_0 src1_sel:DWORD
	s_nop 0
	v_cndmask_b32_e32 v153, v126, v127, vcc
	v_add3_u32 v152, v74, v153, v120
	v_add_u32_e32 v205, v152, v118
	v_add_u32_e32 v206, v152, v119
	ds_read_b64 v[48:49], v205 offset:32768
	ds_read_b64 v[50:51], v206 offset:32768
	ds_read_b64 v[52:53], v205 offset:34816
	ds_read_b64 v[54:55], v206 offset:34816
	v_cmp_gt_u16_sdwa vcc, v35, v128 src0_sel:BYTE_0 src1_sel:DWORD
	s_nop 0
	v_cndmask_b32_e32 v153, v129, v130, vcc
	v_add3_u32 v152, v74, v153, v120
	v_add_u32_e32 v207, v152, v118
	v_add_u32_e32 v208, v152, v119
	ds_read_b64 v[56:57], v207 offset:32768
	ds_read_b64 v[58:59], v208 offset:32768
	ds_read_b64 v[60:61], v207 offset:34816
	ds_read_b64 v[62:63], v208 offset:34816
	v_cmp_gt_u16_sdwa vcc, v35, v131 src0_sel:BYTE_0 src1_sel:DWORD
	s_nop 0
	v_cndmask_b32_e32 v153, v132, v133, vcc
	v_add3_u32 v152, v74, v153, v120
	v_add_u32_e32 v209, v152, v118
	v_add_u32_e32 v210, v152, v119
	v_cmp_gt_u16_sdwa vcc, v35, v134 src0_sel:BYTE_0 src1_sel:DWORD
	s_nop 0
	v_cndmask_b32_e32 v153, v135, v136, vcc
	v_add3_u32 v152, v74, v153, v120
	v_add_u32_e32 v211, v152, v118
	v_add_u32_e32 v212, v152, v119
	v_cmp_gt_u16_sdwa vcc, v35, v137 src0_sel:BYTE_0 src1_sel:DWORD
	s_nop 0
	v_cndmask_b32_e32 v153, v138, v139, vcc
	v_add3_u32 v152, v74, v153, v120
	v_add_u32_e32 v213, v152, v118
	v_add_u32_e32 v214, v152, v119
	v_cmp_gt_u16_sdwa vcc, v35, v140 src0_sel:BYTE_0 src1_sel:DWORD
	s_nop 0
	v_cndmask_b32_e32 v153, v141, v142, vcc
	v_add3_u32 v152, v74, v153, v120
	v_add_u32_e32 v215, v152, v118
	v_add_u32_e32 v216, v152, v119
	v_cmp_gt_u16_sdwa vcc, v35, v143 src0_sel:BYTE_0 src1_sel:DWORD
	s_nop 0
	v_cndmask_b32_e32 v153, v145, v146, vcc
	v_add3_u32 v152, v74, v153, v120
	v_add_u32_e32 v217, v152, v118
	v_add_u32_e32 v218, v152, v119
	v_cvt_pk_bf16_f32 v35, v149, v158
	v_div_scale_f32 v197, s[28:29], v196, v196, 1.0
	s_nop 0
	v_div_scale_f32 v157, vcc, 1.0, v196, 1.0
	v_rcp_f32_e32 v198, v197
	s_mov_b32 s28, s62
	s_nop 1
	v_fma_f32 v154, -v197, v198, 1.0
	v_fmac_f32_e32 v198, v154, v198
	v_mul_f32_e32 v155, v157, v198
	v_fma_f32 v156, -v197, v155, v157
	v_fmac_f32_e32 v155, v156, v198
	v_fma_f32 v156, -v197, v155, v157
	s_nop 1
	v_div_fmas_f32 v155, v156, v198, v155
	v_div_fixup_f32 v74, v155, v196, 1.0
	ds_read_b64 v[64:65], v209 offset:32768
	ds_read_b64 v[66:67], v210 offset:32768
	s_waitcnt lgkmcnt(12)
	v_mfma_f32_16x16x32_bf16 v[160:163], v[40:43], v[8:11], 0
	ds_read_b64 v[68:69], v209 offset:34816
	ds_read_b64 v[70:71], v210 offset:34816
	s_waitcnt lgkmcnt(12)
	v_mfma_f32_16x16x32_bf16 v[164:167], v[44:47], v[8:11], 0
	ds_read_b64 v[176:177], v211 offset:32768
	ds_read_b64 v[178:179], v212 offset:32768
	s_waitcnt lgkmcnt(12)
	v_mfma_f32_16x16x32_bf16 v[160:163], v[48:51], v[12:15], v[160:163]
	ds_read_b64 v[180:181], v211 offset:34816
	ds_read_b64 v[182:183], v212 offset:34816
	s_waitcnt lgkmcnt(12)
	v_mfma_f32_16x16x32_bf16 v[164:167], v[52:55], v[12:15], v[164:167]
	ds_read_b64 v[184:185], v213 offset:32768
	ds_read_b64 v[186:187], v214 offset:32768
	s_waitcnt lgkmcnt(12)
	v_mfma_f32_16x16x32_bf16 v[160:163], v[56:59], v[16:19], v[160:163]
	ds_read_b64 v[188:189], v213 offset:34816
	ds_read_b64 v[190:191], v214 offset:34816
	s_waitcnt lgkmcnt(12)
	v_mfma_f32_16x16x32_bf16 v[164:167], v[60:63], v[16:19], v[164:167]
	ds_read_b64 v[40:41], v215 offset:32768
	ds_read_b64 v[42:43], v216 offset:32768
	s_waitcnt lgkmcnt(12)
	v_mfma_f32_16x16x32_bf16 v[160:163], v[64:67], v[20:23], v[160:163]
	ds_read_b64 v[44:45], v215 offset:34816
	ds_read_b64 v[46:47], v216 offset:34816
	s_waitcnt lgkmcnt(12)
	v_mfma_f32_16x16x32_bf16 v[164:167], v[68:71], v[20:23], v[164:167]
	ds_read_b64 v[48:49], v217 offset:32768
	ds_read_b64 v[50:51], v218 offset:32768
	s_waitcnt lgkmcnt(12)
	v_mfma_f32_16x16x32_bf16 v[160:163], v[176:179], v[24:27], v[160:163]
	ds_read_b64 v[52:53], v217 offset:34816
	ds_read_b64 v[54:55], v218 offset:34816
	s_waitcnt lgkmcnt(12)
; __device__ __forceinline__ unsigned pk2(float lo, float hi) { unsigned r; asm("v_cvt_pk_bf16_f32 %0, %1, %2" : "=v"(r) : "v"(lo), "v"(hi)); return r; }
; __device__ __forceinline__ f32x4 mfma16(bf16x8 a, bf16x8 b, f32x4 c) { return __builtin_amdgcn_mfma_f32_16x16x32_bf16(a, b, c, 0, 0, 0); }
; __device__ __forceinline__ void na_item(const Params& p, int b, int hd, int r, int j, int lane, const float* rpl, const unsigned char* Vl) {
;     ...
; #pragma unroll
;     for (int dt = 0; dt < 4; ++dt) { f32x4 a = (f32x4){0.f, 0.f, 0.f, 0.f};
;         u32x2 va[8], vb[8];
; #pragma unroll
;         for (int ks = 0; ks < 8; ++ks) { int sl = s0 + ks; sl = (sl >= 11) ? sl - 11 : sl; const unsigned char* vp = Vl + sl * 8192 + (16 * dt + fr) * 128;
;             va[ks] = *(const u32x2*)(vp + ca); vb[ks] = *(const u32x2*)(vp + cb); }
; #pragma unroll
;         for (int ks = 0; ks < 8; ++ks) a = mfma16(mk8(va[ks], vb[ks]), pf[ks], a);
;         a = a * rsum; u32x2 wv; wv.x = pk2(a[0], a[1]); wv.y = pk2(a[2], a[3]);
;         *(u32x2*)(yna + tokq * 1024 + hd * 64 + 16 * dt + 4 * fq) = wv; }
	v_mfma_f32_16x16x32_bf16 v[164:167], v[180:183], v[24:27], v[164:167]
	ds_read_b64 v[56:57], v199 offset:36864
	ds_read_b64 v[58:59], v204 offset:36864
	s_waitcnt lgkmcnt(12)
	v_mfma_f32_16x16x32_bf16 v[160:163], v[184:187], v[28:31], v[160:163]
	ds_read_b64 v[60:61], v199 offset:38912
	ds_read_b64 v[62:63], v204 offset:38912
	s_waitcnt lgkmcnt(12)
	v_mfma_f32_16x16x32_bf16 v[164:167], v[188:191], v[28:31], v[164:167]
	ds_read_b64 v[64:65], v205 offset:36864
	ds_read_b64 v[66:67], v206 offset:36864
	s_waitcnt lgkmcnt(12)
	v_mfma_f32_16x16x32_bf16 v[160:163], v[40:43], v[36:39], v[160:163]
	ds_read_b64 v[68:69], v205 offset:38912
	ds_read_b64 v[70:71], v206 offset:38912
	s_waitcnt lgkmcnt(12)
	v_mfma_f32_16x16x32_bf16 v[164:167], v[44:47], v[36:39], v[164:167]
	ds_read_b64 v[176:177], v207 offset:36864
	ds_read_b64 v[178:179], v208 offset:36864
	s_waitcnt lgkmcnt(12)
	v_mfma_f32_16x16x32_bf16 v[160:163], v[48:51], v[32:35], v[160:163]
	ds_read_b64 v[180:181], v207 offset:38912
	ds_read_b64 v[182:183], v208 offset:38912
	s_waitcnt lgkmcnt(12)
	v_mfma_f32_16x16x32_bf16 v[164:167], v[52:55], v[32:35], v[164:167]
	ds_read_b64 v[184:185], v209 offset:36864
	ds_read_b64 v[186:187], v210 offset:36864
	s_waitcnt lgkmcnt(12)
	v_mfma_f32_16x16x32_bf16 v[168:171], v[56:59], v[8:11], 0
	ds_read_b64 v[188:189], v209 offset:38912
	ds_read_b64 v[190:191], v210 offset:38912
	s_waitcnt lgkmcnt(12)
	v_mfma_f32_16x16x32_bf16 v[172:175], v[60:63], v[8:11], 0
	ds_read_b64 v[40:41], v211 offset:36864
	ds_read_b64 v[42:43], v212 offset:36864
	s_waitcnt lgkmcnt(12)
	v_mfma_f32_16x16x32_bf16 v[168:171], v[64:67], v[12:15], v[168:171]
	ds_read_b64 v[44:45], v211 offset:38912
	ds_read_b64 v[46:47], v212 offset:38912
	s_waitcnt lgkmcnt(12)
	v_mfma_f32_16x16x32_bf16 v[172:175], v[68:71], v[12:15], v[172:175]
	s_nop 7
	v_pk_mul_f32 v[160:161], v[74:75], v[160:161] op_sel_hi:[0,1]
	v_pk_mul_f32 v[162:163], v[74:75], v[162:163] op_sel_hi:[0,1]
	v_cvt_pk_bf16_f32 v202, v160, v161
	v_cvt_pk_bf16_f32 v203, v162, v163
	global_store_dwordx2 v[200:201], v[202:203], off offset:-64
	v_pk_mul_f32 v[164:165], v[74:75], v[164:165] op_sel_hi:[0,1]
	v_pk_mul_f32 v[166:167], v[74:75], v[166:167] op_sel_hi:[0,1]
	v_cvt_pk_bf16_f32 v12, v164, v165
	v_cvt_pk_bf16_f32 v13, v166, v167
	global_store_dwordx2 v[200:201], v[12:13], off offset:-32
	ds_read_b64 v[48:49], v213 offset:36864
	ds_read_b64 v[50:51], v214 offset:36864
	s_waitcnt lgkmcnt(12)
	v_mfma_f32_16x16x32_bf16 v[168:171], v[176:179], v[16:19], v[168:171]
	ds_read_b64 v[52:53], v213 offset:38912
	ds_read_b64 v[54:55], v214 offset:38912
	s_waitcnt lgkmcnt(12)
	v_mfma_f32_16x16x32_bf16 v[172:175], v[180:183], v[16:19], v[172:175]
	ds_read_b64 v[56:57], v215 offset:36864
	ds_read_b64 v[58:59], v216 offset:36864
	s_waitcnt lgkmcnt(12)
	v_mfma_f32_16x16x32_bf16 v[168:171], v[184:187], v[20:23], v[168:171]
	ds_read_b64 v[60:61], v215 offset:38912
	ds_read_b64 v[62:63], v216 offset:38912
	s_waitcnt lgkmcnt(12)
	v_mfma_f32_16x16x32_bf16 v[172:175], v[188:191], v[20:23], v[172:175]
	ds_read_b64 v[64:65], v217 offset:36864
	ds_read_b64 v[66:67], v218 offset:36864
	s_waitcnt lgkmcnt(12)
	v_mfma_f32_16x16x32_bf16 v[168:171], v[40:43], v[24:27], v[168:171]
	ds_read_b64 v[68:69], v217 offset:38912
	ds_read_b64 v[70:71], v218 offset:38912
	s_waitcnt lgkmcnt(12)
	v_mfma_f32_16x16x32_bf16 v[172:175], v[44:47], v[24:27], v[172:175]
	s_waitcnt lgkmcnt(10)
	v_mfma_f32_16x16x32_bf16 v[168:171], v[48:51], v[28:31], v[168:171]
	s_waitcnt lgkmcnt(8)
	v_mfma_f32_16x16x32_bf16 v[172:175], v[52:55], v[28:31], v[172:175]
	s_waitcnt lgkmcnt(6)
	v_mfma_f32_16x16x32_bf16 v[168:171], v[56:59], v[36:39], v[168:171]
	s_waitcnt lgkmcnt(4)
	v_mfma_f32_16x16x32_bf16 v[172:175], v[60:63], v[36:39], v[172:175]
	s_waitcnt lgkmcnt(2)
	v_mfma_f32_16x16x32_bf16 v[168:171], v[64:67], v[32:35], v[168:171]
	s_waitcnt lgkmcnt(0)
	v_mfma_f32_16x16x32_bf16 v[172:175], v[68:71], v[32:35], v[172:175]
	s_nop 7
	s_nop 3
	v_pk_mul_f32 v[168:169], v[74:75], v[168:169] op_sel_hi:[0,1]
	v_pk_mul_f32 v[170:171], v[74:75], v[170:171] op_sel_hi:[0,1]
	v_cvt_pk_bf16_f32 v14, v168, v169
	v_cvt_pk_bf16_f32 v15, v170, v171
	global_store_dwordx2 v[200:201], v[14:15], off
	v_pk_mul_f32 v[172:173], v[74:75], v[172:173] op_sel_hi:[0,1]
	v_pk_mul_f32 v[174:175], v[74:75], v[174:175] op_sel_hi:[0,1]
	v_cvt_pk_bf16_f32 v8, v172, v173
	v_cvt_pk_bf16_f32 v9, v174, v175
	global_store_dwordx2 v[200:201], v[8:9], off offset:32
	s_cbranch_scc1 .LBB0_320
